# v91 + GDN scan step second half: the state and output accumulation MFMA pairs alternate (no MFMA directly behind the one it accumulates onto); same accumulation order
# baseline (speedup 1.0000x reference)
; __device__ __forceinline__ void chain_load(ChainOps& o, const GdnP& P, int b, int h, int n, int w, int mt, int nh, int lane, int tid) {
;     const int l15 = lane & 15, quad = lane >> 4;
;     const int cn = b * 64 + n, unit = cn * 8 + h, row0 = cn * 64;
;     const bf16_t* wrow = P.wbuf + (size_t)unit * 8192 + (mt * 16 + l15) * 128 + quad * 8;
;     const bf16_t* qrow = P.proj + (size_t)(row0 + mt * 16 + l15) * NIN + C_GDN + h * 128 + quad * 8;
; #pragma unroll
;     for (int s = 0; s < 4; ++s) { o.wf[s] = *(const bf16x8*)(wrow + 32 * s); o.qf[s] = *(const bf16x8*)(qrow + 32 * s); }
;     const bf16_t* arow = P.attnb + (size_t)unit * 4096 + (mt * 16 + l15) * 64 + quad * 8;
;     const int kidx = w * 16 + l15;
;     const bf16_t* krow = P.proj + (size_t)(row0 + (kidx >> 1)) * NIN + C_GDN + 1024 + h * 128 + (kidx & 1) * 64 + quad * 8;
; #pragma unroll
;     for (int s = 0; s < 2; ++s) { o.af[s] = *(const bf16x8*)(arow + 32 * s); o.kf[s] = *(const bf16x8*)(krow + 32 * s); }
;     o.cd = P.cdb[unit];
;     const int cb = ((mt * 2 + nh) * 64 + lane) * 2;
;     const bf16_t* up = P.proj + (size_t)(row0 + (cb >> 4)) * NIN + C_GDN + 2048 + h * 128 + (cb & 15) * 8;
;     o.uf[0] = *(const u32x4*)up; o.uf[1] = *(const u32x4*)(up + 8);
; __device__ __forceinline__ void gdn_chain(LAS unsigned char* lds, const GdnP& P, const float* out_norm, int bh, const int tid) {
;     ...
;     for (int n = 0; n < 64; ++n) {
;         const int row0 = (b * 64 + n) * 64;
;         chain_load(nxt, P, b, h, n < 63 ? n + 1 : n, w, mt, nh, lane, tid);
;         f32x4 oacc[4];
; #pragma unroll
;         for (int q = 0; q < 4; ++q) { const int nt = 4 * nh + q; f32x4 a1 = (f32x4){0.f, 0.f, 0.f, 0.f}; oacc[q] = (f32x4){0.f, 0.f, 0.f, 0.f};
; #pragma unroll
;             for (int s = 0; s < 4; ++s) { const bf16x8 sf = *(const LAS bf16x8*)(lds + GC_ST + (nt * 16 + l15) * 272 + (quad * 8 + 32 * s) * 2);
;                 a1 = __builtin_amdgcn_mfma_f32_16x16x32_bf16(cur.wf[s], sf, a1, 0, 0, 0); oacc[q] = __builtin_amdgcn_mfma_f32_16x16x32_bf16(cur.qf[s], sf, oacc[q], 0, 0, 0); }
;             const unsigned u01 = cur.uf[q >> 1][(q & 1) * 2], u23 = cur.uf[q >> 1][(q & 1) * 2 + 1];
;             u32x2 pv; pv.x = pk2(bflo(u01) - a1[0], bfhi(u01) - a1[1]); pv.y = pk2(bflo(u23) - a1[2], bfhi(u23) - a1[3]);
;             *(LAS u32x2*)(lds + GC_VT + (nt * 16 + l15) * 144 + (mt * 16 + quad * 4) * 2) = pv; }
.LBB0_1126:
	s_waitcnt vmcnt(14)
	v_mov_b64_e32 v[90:91], v[74:75]
	v_mov_b64_e32 v[88:89], v[72:73]
	ds_read_b128 v[72:75], v161
	ds_read_b128 v[92:95], v161 offset:64
	s_waitcnt vmcnt(13)
	v_mov_b64_e32 v[106:107], v[14:15]
	v_mov_b64_e32 v[104:105], v[12:13]
	s_waitcnt vmcnt(10)
	v_mov_b64_e32 v[110:111], v[22:23]
	s_waitcnt lgkmcnt(1)
	v_mfma_f32_16x16x32_bf16 v[96:99], v[88:91], v[72:75], 0
	s_waitcnt vmcnt(8)
	v_mov_b64_e32 v[102:103], v[30:31]
	v_mov_b64_e32 v[108:109], v[20:21]
	ds_read_b128 v[20:23], v161 offset:128
	v_mov_b64_e32 v[100:101], v[28:29]
	s_waitcnt lgkmcnt(1)
	v_mfma_f32_16x16x32_bf16 v[28:31], v[104:107], v[92:95], v[96:99]
	v_mov_b64_e32 v[180:181], v[18:19]
	v_mov_b64_e32 v[184:185], v[6:7]
	v_mov_b64_e32 v[178:179], v[16:17]
	v_mov_b64_e32 v[182:183], v[4:5]
	ds_read_b128 v[4:7], v161 offset:192
	s_waitcnt lgkmcnt(1)
	v_mfma_f32_16x16x32_bf16 v[16:19], v[108:111], v[20:23], v[28:31]
	v_mov_b64_e32 v[188:189], v[2:3]
	v_mov_b64_e32 v[186:187], v[0:1]
	s_waitcnt vmcnt(7)
	v_mov_b64_e32 v[192:193], v[10:11]
	v_mfma_f32_16x16x32_bf16 v[12:15], v[100:103], v[72:75], 0
	v_mov_b64_e32 v[190:191], v[8:9]
	s_waitcnt vmcnt(3)
	v_lshlrev_b32_e32 v8, 16, v80
	v_and_b32_e32 v9, 0xffff0000, v80
	s_waitcnt lgkmcnt(0)
	v_mfma_f32_16x16x32_bf16 v[0:3], v[178:181], v[4:7], v[16:19]
	s_add_i32 s0, s47, 0x41
	s_cmp_lg_u32 s47, -1
	s_cselect_b32 s0, s0, 63
	s_add_i32 s0, s0, s44
	s_lshl_b32 s30, s0, 3
	s_nop 2
	v_pk_add_f32 v[0:1], v[8:9], v[0:1] neg_lo:[0,1] neg_hi:[0,1]
	v_mfma_f32_16x16x32_bf16 v[8:11], v[182:185], v[92:95], v[12:15]
	v_cvt_pk_bf16_f32 v0, v0, v1
	s_or_b32 s30, s30, s43
	s_lshl_b32 s50, s0, 6
	v_lshlrev_b32_e32 v12, 16, v81
	v_and_b32_e32 v13, 0xffff0000, v81
	v_pk_add_f32 v[2:3], v[12:13], v[2:3] neg_lo:[0,1] neg_hi:[0,1]
	v_mfma_f32_16x16x32_bf16 v[8:11], v[186:189], v[20:23], v[8:11]
	v_cvt_pk_bf16_f32 v1, v2, v3
	v_add_u32_e32 v2, v155, v156
	ds_write_b64 v2, v[0:1] offset:34816
	ds_read_b128 v[0:3], v162
	v_mfma_f32_16x16x32_bf16 v[198:201], v[190:193], v[4:7], v[8:11]
	ds_read_b128 v[4:7], v162 offset:64
	ds_read_b128 v[12:15], v162 offset:128
	s_ashr_i32 s31, s30, 31
	s_waitcnt lgkmcnt(2)
	v_mfma_f32_16x16x32_bf16 v[8:11], v[88:91], v[0:3], 0
	v_mov_b64_e32 v[94:95], v[38:39]
	s_lshl_b64 s[48:49], s[30:31], 14
	v_or_b32_e32 v18, s50, v152
	v_mfma_f32_16x16x32_bf16 v[0:3], v[100:103], v[0:3], 0
	v_mov_b64_e32 v[202:203], s[16:17]
	v_mov_b64_e32 v[92:93], v[36:37]
	v_lshl_add_u64 v[16:17], v[132:133], 0, s[48:49]
	s_waitcnt lgkmcnt(1)
	v_mfma_f32_16x16x32_bf16 v[8:11], v[104:107], v[4:7], v[8:11]
	s_lshl_b32 s0, s45, 1
	v_mov_b64_e32 v[196:197], v[70:71]
	v_mov_b64_e32 v[194:195], v[68:69]
	v_mfma_f32_16x16x32_bf16 v[0:3], v[182:185], v[4:7], v[0:3]
	ds_read_b128 v[4:7], v162 offset:192
	v_mov_b64_e32 v[208:209], v[46:47]
	v_mov_b64_e32 v[98:99], v[50:51]
	s_waitcnt lgkmcnt(1)
	v_mfma_f32_16x16x32_bf16 v[8:11], v[108:111], v[12:15], v[8:11]
	v_mov_b64_e32 v[206:207], v[44:45]
	v_mov_b64_e32 v[96:97], v[48:49]
	v_add_u32_e32 v80, s50, v153
	s_waitcnt lgkmcnt(0)
	v_mfma_f32_16x16x32_bf16 v[8:11], v[178:181], v[4:7], v[8:11]
	v_mov_b32_e32 v138, v123
	v_mov_b32_e32 v123, v115
	v_mov_b32_e32 v127, v115
	v_mfma_f32_16x16x32_bf16 v[0:3], v[186:189], v[12:15], v[0:3]
	v_lshlrev_b32_e32 v14, 16, v82
	v_and_b32_e32 v15, 0xffff0000, v82
	s_nop 1
	v_pk_add_f32 v[8:9], v[14:15], v[8:9] neg_lo:[0,1] neg_hi:[0,1]
	v_lshlrev_b32_e32 v14, 16, v83
	v_and_b32_e32 v15, 0xffff0000, v83
	v_pk_add_f32 v[10:11], v[14:15], v[10:11] neg_lo:[0,1] neg_hi:[0,1]
	v_cvt_pk_bf16_f32 v8, v8, v9
	v_cvt_pk_bf16_f32 v9, v10, v11
	v_add_u32_e32 v10, v155, v157
	ds_write_b64 v10, v[8:9] offset:34816
	ds_read_b128 v[8:11], v163
	ds_read_b128 v[36:39], v163 offset:64
	v_mad_i64_i32 v[12:13], s[48:49], v18, s40, v[202:203]
	v_lshl_add_u64 v[12:13], v[12:13], 0, s[0:1]
	s_waitcnt lgkmcnt(1)
	v_mfma_f32_16x16x32_bf16 v[28:31], v[88:91], v[8:11], 0
	s_lshl_b64 s[48:49], s[30:31], 13
	v_lshl_add_u64 v[218:219], v[134:135], 0, s[48:49]
	v_mad_i64_i32 v[80:81], s[48:49], v80, s40, v[202:203]
	v_mfma_f32_16x16x32_bf16 v[210:213], v[190:193], v[4:7], v[0:3]
	s_lshl_b64 s[30:31], s[30:31], 2
	s_add_u32 s30, s2, s30
	s_addc_u32 s31, s3, s31
	v_lshl_add_u64 v[0:1], v[12:13], 0, v[114:115]
	v_add_co_u32_e32 v70, vcc, s41, v0
	v_lshl_add_u64 v[68:69], v[0:1], 0, s[22:23]
	s_nop 0
	v_addc_co_u32_e32 v71, vcc, 0, v1, vcc
	global_load_dwordx4 v[72:75], v[16:17], off
	global_load_dwordx4 v[12:15], v[16:17], off offset:64
	v_mfma_f32_16x16x32_bf16 v[44:47], v[100:103], v[8:11], 0
	global_load_dwordx4 v[4:7], v[68:69], off offset:64
	global_load_dwordx4 v[0:3], v[68:69], off offset:128
	global_load_dwordx4 v[20:23], v[16:17], off offset:128
	s_nop 0
	global_load_dwordx4 v[16:19], v[16:17], off offset:192
	v_pk_mul_f32 v[66:67], v[66:67], v[138:139] op_sel_hi:[1,0]
	v_pk_mul_f32 v[64:65], v[64:65], v[138:139] op_sel_hi:[1,0]
	s_waitcnt lgkmcnt(0)
	v_mfma_f32_16x16x32_bf16 v[48:51], v[104:107], v[36:39], v[28:31]
	s_nop 2
	global_load_dwordx4 v[28:31], v[70:71], off offset:2048
	global_load_dwordx4 v[8:11], v[68:69], off offset:192
	ds_read_b128 v[68:71], v163 offset:128
	v_pk_mul_f32 v[62:63], v[62:63], v[138:139] op_sel_hi:[1,0]
	v_mfma_f32_16x16x32_bf16 v[36:39], v[182:185], v[36:39], v[44:47]
	v_mul_f32_e64 v60, v60, v138
	v_mul_f32_e64 v61, v61, v138
	v_pk_mul_f32 v[58:59], v[58:59], v[138:139] op_sel_hi:[1,0]
	v_pk_mul_f32 v[56:57], v[56:57], v[138:139] op_sel_hi:[1,0]
	ds_read_b128 v[44:47], v163 offset:192
	s_waitcnt lgkmcnt(1)
; #define LAS __attribute__((address_space(3)))
; __device__ __forceinline__ unsigned f2bf(float f) { return pk2(f, 0.f) & 0xffffu; }
; __device__ __forceinline__ void chain_load(ChainOps& o, const GdnP& P, int b, int h, int n, int w, int mt, int nh, int lane, int tid) {
;     ...
;     for (int s = 0; s < 4; ++s) { o.wf[s] = *(const bf16x8*)(wrow + 32 * s); o.qf[s] = *(const bf16x8*)(qrow + 32 * s); }
;     const bf16_t* arow = P.attnb + (size_t)unit * 4096 + (mt * 16 + l15) * 64 + quad * 8;
;     const int kidx = w * 16 + l15;
;     const bf16_t* krow = P.proj + (size_t)(row0 + (kidx >> 1)) * NIN + C_GDN + 1024 + h * 128 + (kidx & 1) * 64 + quad * 8;
; #pragma unroll
;     for (int s = 0; s < 2; ++s) { o.af[s] = *(const bf16x8*)(arow + 32 * s); o.kf[s] = *(const bf16x8*)(krow + 32 * s); }
;     o.cd = P.cdb[unit];
;     const int cb = ((mt * 2 + nh) * 64 + lane) * 2;
;     const bf16_t* up = P.proj + (size_t)(row0 + (cb >> 4)) * NIN + C_GDN + 2048 + h * 128 + (cb & 15) * 8;
;     o.uf[0] = *(const u32x4*)up; o.uf[1] = *(const u32x4*)(up + 8);
; __device__ __forceinline__ void gdn_chain(LAS unsigned char* lds, const GdnP& P, const float* out_norm, int bh, const int tid) {
;     ...
;         lds_barrier();
;         float ss[4] = {0.f, 0.f, 0.f, 0.f};
; #pragma unroll
;         for (int q = 0; q < 4; ++q) { const int nt = 4 * nh + q;
; #pragma unroll
;             for (int s = 0; s < 2; ++s) { const bf16x8 vf = *(const LAS bf16x8*)(lds + GC_VT + (nt * 16 + l15) * 144 + (quad * 8 + 32 * s) * 2); oacc[q] = __builtin_amdgcn_mfma_f32_16x16x32_bf16(cur.af[s], vf, oacc[q], 0, 0, 0); }
; #pragma unroll
;             for (int i = 0; i < 4; ++i) { ss[i] += oacc[q][i] * oacc[q][i]; *(LAS bf16_t*)(lds + GC_OB + (mt * 16 + quad * 4 + i) * 272 + (nt * 16 + l15) * 2) = (bf16_t)f2bf(oacc[q][i]); } }
; #pragma unroll
;         for (int nt = 0; nt < 8; ++nt) { sacc[nt] = sacc[nt] * cur.cd;
; #pragma unroll
;             for (int s = 0; s < 2; ++s) { const bf16x8 vf = *(const LAS bf16x8*)(lds + GC_VT + (nt * 16 + l15) * 144 + (quad * 8 + 32 * s) * 2); sacc[nt] = __builtin_amdgcn_mfma_f32_16x16x32_bf16(cur.kf[s], vf, sacc[nt], 0, 0, 0); }
;             u32x2 pv; pv.x = pk2(sacc[nt][0], sacc[nt][1]); pv.y = pk2(sacc[nt][2], sacc[nt][3]);
;             *(LAS u32x2*)(lds + GC_ST + (nt * 16 + l15) * 272 + (w * 16 + quad * 4) * 2) = pv; }
	v_mfma_f32_16x16x32_bf16 v[48:51], v[108:111], v[68:71], v[48:51]
	v_mul_f32_e64 v54, v54, v138
	v_mul_f32_e64 v55, v55, v138
	v_pk_mul_f32 v[52:53], v[52:53], v[138:139] op_sel_hi:[1,0]
	v_pk_mul_f32 v[42:43], v[42:43], v[138:139] op_sel_hi:[1,0]
	s_waitcnt lgkmcnt(0)
	v_mfma_f32_16x16x32_bf16 v[48:51], v[178:181], v[44:47], v[48:51]
	v_mul_f32_e64 v40, v40, v138
	v_mul_f32_e64 v41, v41, v138
	v_pk_mul_f32 v[34:35], v[34:35], v[138:139] op_sel_hi:[1,0]
	v_pk_mul_f32 v[32:33], v[32:33], v[138:139] op_sel_hi:[1,0]
	v_mfma_f32_16x16x32_bf16 v[36:39], v[186:189], v[68:71], v[36:39]
	s_waitcnt vmcnt(10)
	v_lshlrev_b32_e32 v70, 16, v84
	v_and_b32_e32 v71, 0xffff0000, v84
	v_pk_add_f32 v[48:49], v[70:71], v[48:49] neg_lo:[0,1] neg_hi:[0,1]
	v_lshlrev_b32_e32 v70, 16, v85
	v_and_b32_e32 v71, 0xffff0000, v85
	v_pk_add_f32 v[50:51], v[70:71], v[50:51] neg_lo:[0,1] neg_hi:[0,1]
	v_cvt_pk_bf16_f32 v48, v48, v49
	v_cvt_pk_bf16_f32 v49, v50, v51
	v_add_u32_e32 v50, v155, v158
	ds_write_b64 v50, v[48:49] offset:34816
	ds_read_b128 v[48:51], v164
	v_lshl_add_u64 v[68:69], v[80:81], 0, s[0:1]
	ds_read_b128 v[80:83], v164 offset:64
	v_lshl_add_u64 v[68:69], v[68:69], 0, v[122:123]
	s_waitcnt lgkmcnt(1)
	v_mfma_f32_16x16x32_bf16 v[88:91], v[88:91], v[48:51], 0
	v_add_u32_e32 v84, s50, v154
	v_pk_mul_f32 v[26:27], v[26:27], v[138:139] op_sel_hi:[1,0]
	v_pk_mul_f32 v[24:25], v[24:25], v[138:139] op_sel_hi:[1,0]
	v_mfma_f32_16x16x32_bf16 v[214:217], v[190:193], v[44:47], v[36:39]
	v_mul_f32_e64 v78, v78, v138
	v_mul_f32_e64 v79, v79, v138
	v_pk_mul_f32 v[76:77], v[76:77], v[138:139] op_sel_hi:[1,0]
	v_lshl_add_u64 v[36:37], v[68:69], 0, v[114:115]
	v_lshl_add_u64 v[38:39], v[36:37], 0, s[24:25]
	v_add_co_u32_e32 v36, vcc, s38, v36
	global_load_dwordx4 v[68:71], v[218:219], off
	global_load_dwordx4 v[44:47], v[218:219], off offset:64
	v_addc_co_u32_e32 v37, vcc, 0, v37, vcc
	v_mfma_f32_16x16x32_bf16 v[100:103], v[100:103], v[48:51], 0
	global_load_dwordx4 v[48:51], v[36:37], off
	s_nop 0
	global_load_dwordx4 v[36:39], v[38:39], off offset:64
	s_nop 0
	global_load_dword v123, v115, s[30:31]
	s_waitcnt lgkmcnt(0)
	v_mfma_f32_16x16x32_bf16 v[88:91], v[104:107], v[80:83], v[88:91]
	ds_read_b128 v[104:107], v164 offset:128
	v_mad_i64_i32 v[84:85], s[30:31], v84, s40, v[202:203]
	v_mfma_f32_16x16x32_bf16 v[80:83], v[182:185], v[80:83], v[100:103]
	v_lshl_add_u64 v[84:85], v[84:85], 0, s[0:1]
	s_nop 1
	ds_read_b128 v[100:103], v164 offset:192
	s_waitcnt lgkmcnt(1)
	v_mfma_f32_16x16x32_bf16 v[88:91], v[108:111], v[104:107], v[88:91]
	v_mfma_f32_16x16x32_bf16 v[104:107], v[186:189], v[104:107], v[80:83]
	s_nop 2
	v_lshl_add_u64 v[80:81], v[84:85], 0, v[126:127]
	s_waitcnt lgkmcnt(0)
	v_mfma_f32_16x16x32_bf16 v[108:111], v[178:181], v[100:103], v[88:91]
	v_lshl_add_u64 v[84:85], v[80:81], 0, s[26:27]
	v_add_co_u32_e32 v80, vcc, s38, v80
	v_mfma_f32_16x16x32_bf16 v[178:181], v[190:193], v[100:103], v[104:107]
	s_nop 0
	v_addc_co_u32_e32 v81, vcc, 0, v81, vcc
	global_load_dwordx4 v[80:83], v[80:81], off offset:2048
	s_nop 0
	global_load_dwordx4 v[88:91], v[84:85], off offset:16
	v_lshlrev_b32_e32 v84, 16, v86
	v_and_b32_e32 v85, 0xffff0000, v86
	v_lshlrev_b32_e32 v86, 16, v87
	v_and_b32_e32 v87, 0xffff0000, v87
	v_pk_add_f32 v[84:85], v[84:85], v[108:109] neg_lo:[0,1] neg_hi:[0,1]
	v_pk_add_f32 v[86:87], v[86:87], v[110:111] neg_lo:[0,1] neg_hi:[0,1]
	v_cvt_pk_bf16_f32 v84, v84, v85
	v_cvt_pk_bf16_f32 v85, v86, v87
	v_add_u32_e32 v86, v155, v159
	ds_write_b64 v86, v[84:85] offset:34816
	s_waitcnt lgkmcnt(0)
	s_barrier
	ds_read_b128 v[182:185], v148 offset:34816
	ds_read_b128 v[186:189], v148 offset:34880
	ds_read_b128 v[190:193], v148 offset:37120
	ds_read_b128 v[232:235], v148 offset:37184
	s_waitcnt lgkmcnt(2)
	s_cmp_lg_u32 s59, 0
	s_cbranch_scc1 .Lcb_no0
	v_mfma_f32_16x16x32_bf16 v[64:67], v[96:99], v[182:185], v[64:67]
	v_mfma_f32_16x16x32_bf16 v[84:87], v[194:197], v[182:185], v[198:201]
	v_mfma_f32_16x16x32_bf16 v[64:67], v[92:95], v[186:189], v[64:67]
	v_mfma_f32_16x16x32_bf16 v[84:87], v[206:209], v[186:189], v[84:87]
	s_branch .Lcb_skip0
.Lcb_no0:
	v_mfma_f32_16x16x32_bf16 v[64:67], v[96:99], v[182:185], v[64:67]
	v_mfma_f32_16x16x32_bf16 v[64:67], v[92:95], v[186:189], v[64:67]
.Lcb_skip0:
	ds_read_b128 v[182:185], v148 offset:39424
	ds_read_b128 v[186:189], v148 offset:39488
	s_waitcnt lgkmcnt(2)
	s_cmp_lg_u32 s59, 0
	s_cbranch_scc1 .Lcb_no1
	v_mfma_f32_16x16x32_bf16 v[60:63], v[96:99], v[190:193], v[60:63]
	v_mfma_f32_16x16x32_bf16 v[100:103], v[194:197], v[190:193], v[210:213]
	v_mfma_f32_16x16x32_bf16 v[60:63], v[92:95], v[232:235], v[60:63]
	v_mfma_f32_16x16x32_bf16 v[100:103], v[206:209], v[232:235], v[100:103]
	s_branch .Lcb_skip1
; #define LAS __attribute__((address_space(3)))
; __device__ __forceinline__ unsigned pk2(float lo, float hi) { const f32x2 v = {lo, hi}; return __builtin_bit_cast(unsigned, __builtin_convertvector(v, hbf2)); }
; __device__ __forceinline__ unsigned f2bf(float f) { return pk2(f, 0.f) & 0xffffu; }
; __device__ __forceinline__ void gdn_chain(LAS unsigned char* lds, const GdnP& P, const float* out_norm, int bh, const int tid) {
;     ...
;         for (int q = 0; q < 4; ++q) { const int nt = 4 * nh + q;
; #pragma unroll
;             for (int s = 0; s < 2; ++s) { const bf16x8 vf = *(const LAS bf16x8*)(lds + GC_VT + (nt * 16 + l15) * 144 + (quad * 8 + 32 * s) * 2); oacc[q] = __builtin_amdgcn_mfma_f32_16x16x32_bf16(cur.af[s], vf, oacc[q], 0, 0, 0); }
; #pragma unroll
;             for (int i = 0; i < 4; ++i) { ss[i] += oacc[q][i] * oacc[q][i]; *(LAS bf16_t*)(lds + GC_OB + (mt * 16 + quad * 4 + i) * 272 + (nt * 16 + l15) * 2) = (bf16_t)f2bf(oacc[q][i]); } }
; #pragma unroll
;         for (int nt = 0; nt < 8; ++nt) { sacc[nt] = sacc[nt] * cur.cd;
; #pragma unroll
;             for (int s = 0; s < 2; ++s) { const bf16x8 vf = *(const LAS bf16x8*)(lds + GC_VT + (nt * 16 + l15) * 144 + (quad * 8 + 32 * s) * 2); sacc[nt] = __builtin_amdgcn_mfma_f32_16x16x32_bf16(cur.kf[s], vf, sacc[nt], 0, 0, 0); }
;             u32x2 pv; pv.x = pk2(sacc[nt][0], sacc[nt][1]); pv.y = pk2(sacc[nt][2], sacc[nt][3]);
;             *(LAS u32x2*)(lds + GC_ST + (nt * 16 + l15) * 272 + (w * 16 + quad * 4) * 2) = pv; }
.Lcb_no1:
	v_mfma_f32_16x16x32_bf16 v[60:63], v[96:99], v[190:193], v[60:63]
	v_mfma_f32_16x16x32_bf16 v[60:63], v[92:95], v[232:235], v[60:63]
.Lcb_skip1:
	ds_read_b128 v[190:193], v148 offset:41728
	ds_read_b128 v[232:235], v148 offset:41792
	v_cvt_pk_bf16_f32 v218, v64, v65
	v_cvt_pk_bf16_f32 v219, v66, v67
	ds_write_b64 v169, v[218:219]
	s_waitcnt lgkmcnt(3)
	s_cmp_lg_u32 s59, 0
	s_cbranch_scc1 .Lcb_no2
	v_mfma_f32_16x16x32_bf16 v[56:59], v[96:99], v[182:185], v[56:59]
	v_mfma_f32_16x16x32_bf16 v[104:107], v[194:197], v[182:185], v[214:217]
	v_mfma_f32_16x16x32_bf16 v[56:59], v[92:95], v[186:189], v[56:59]
	v_mfma_f32_16x16x32_bf16 v[104:107], v[206:209], v[186:189], v[104:107]
	s_branch .Lcb_skip2
.Lcb_no2:
	v_mfma_f32_16x16x32_bf16 v[56:59], v[96:99], v[182:185], v[56:59]
	v_mfma_f32_16x16x32_bf16 v[56:59], v[92:95], v[186:189], v[56:59]
.Lcb_skip2:
	ds_read_b128 v[182:185], v148 offset:44032
	ds_read_b128 v[186:189], v148 offset:44096
	v_cvt_pk_bf16_f32 v218, v60, v61
	v_cvt_pk_bf16_f32 v219, v62, v63
	ds_write_b64 v169, v[218:219] offset:4352
	s_waitcnt lgkmcnt(4)
	s_cmp_lg_u32 s59, 0
	s_cbranch_scc1 .Lcb_no3
	v_mfma_f32_16x16x32_bf16 v[52:55], v[96:99], v[190:193], v[52:55]
	v_mfma_f32_16x16x32_bf16 v[108:111], v[194:197], v[190:193], v[178:181]
	v_mfma_f32_16x16x32_bf16 v[52:55], v[92:95], v[232:235], v[52:55]
	v_mfma_f32_16x16x32_bf16 v[108:111], v[206:209], v[232:235], v[108:111]
	s_branch .Lcb_skip3
.Lcb_no3:
	v_mfma_f32_16x16x32_bf16 v[52:55], v[96:99], v[190:193], v[52:55]
	v_mfma_f32_16x16x32_bf16 v[52:55], v[92:95], v[232:235], v[52:55]
.Lcb_skip3:
	ds_read_b128 v[190:193], v148 offset:46336
	ds_read_b128 v[232:235], v148 offset:46400
	v_cvt_pk_bf16_f32 v218, v56, v57
	v_cvt_pk_bf16_f32 v219, v58, v59
	ds_write_b64 v169, v[218:219] offset:8704
	s_waitcnt lgkmcnt(4)
	s_cmp_lg_u32 s59, 1
	s_cbranch_scc1 .Lcb_no4
	v_mfma_f32_16x16x32_bf16 v[40:43], v[96:99], v[182:185], v[40:43]
	v_mfma_f32_16x16x32_bf16 v[84:87], v[194:197], v[182:185], v[198:201]
	v_mfma_f32_16x16x32_bf16 v[40:43], v[92:95], v[186:189], v[40:43]
	v_mfma_f32_16x16x32_bf16 v[84:87], v[206:209], v[186:189], v[84:87]
	s_branch .Lcb_skip4
.Lcb_no4:
	v_mfma_f32_16x16x32_bf16 v[40:43], v[96:99], v[182:185], v[40:43]
	v_mfma_f32_16x16x32_bf16 v[40:43], v[92:95], v[186:189], v[40:43]
.Lcb_skip4:
	ds_read_b128 v[182:185], v148 offset:48640
	ds_read_b128 v[186:189], v148 offset:48704
	v_cvt_pk_bf16_f32 v218, v52, v53
	v_cvt_pk_bf16_f32 v219, v54, v55
	ds_write_b64 v169, v[218:219] offset:13056
	s_waitcnt lgkmcnt(4)
	s_cmp_lg_u32 s59, 1
	s_cbranch_scc1 .Lcb_no5
	v_mfma_f32_16x16x32_bf16 v[32:35], v[96:99], v[190:193], v[32:35]
	v_mfma_f32_16x16x32_bf16 v[100:103], v[194:197], v[190:193], v[210:213]
	v_mfma_f32_16x16x32_bf16 v[32:35], v[92:95], v[232:235], v[32:35]
	v_mfma_f32_16x16x32_bf16 v[100:103], v[206:209], v[232:235], v[100:103]
	s_branch .Lcb_skip5
.Lcb_no5:
	v_mfma_f32_16x16x32_bf16 v[32:35], v[96:99], v[190:193], v[32:35]
	v_mfma_f32_16x16x32_bf16 v[32:35], v[92:95], v[232:235], v[32:35]
.Lcb_skip5:
	ds_read_b128 v[190:193], v148 offset:50944
	ds_read_b128 v[232:235], v148 offset:51008
	v_cvt_pk_bf16_f32 v218, v40, v41
	v_cvt_pk_bf16_f32 v219, v42, v43
	ds_write_b64 v169, v[218:219] offset:17408
	s_waitcnt lgkmcnt(4)
	s_cmp_lg_u32 s59, 1
	s_cbranch_scc1 .Lcb_no6
	v_mfma_f32_16x16x32_bf16 v[24:27], v[96:99], v[182:185], v[24:27]
	v_mfma_f32_16x16x32_bf16 v[104:107], v[194:197], v[182:185], v[214:217]
	v_mfma_f32_16x16x32_bf16 v[24:27], v[92:95], v[186:189], v[24:27]
	v_mfma_f32_16x16x32_bf16 v[104:107], v[206:209], v[186:189], v[104:107]
	s_branch .Lcb_skip6
.Lcb_no6:
	v_mfma_f32_16x16x32_bf16 v[24:27], v[96:99], v[182:185], v[24:27]
	v_mfma_f32_16x16x32_bf16 v[24:27], v[92:95], v[186:189], v[24:27]
.Lcb_skip6:
	v_cvt_pk_bf16_f32 v218, v32, v33
	v_cvt_pk_bf16_f32 v219, v34, v35
	ds_write_b64 v169, v[218:219] offset:21760
	s_waitcnt lgkmcnt(2)
	s_cmp_lg_u32 s59, 1
	s_cbranch_scc1 .Lcb_no7
	v_mfma_f32_16x16x32_bf16 v[76:79], v[96:99], v[190:193], v[76:79]
	v_mfma_f32_16x16x32_bf16 v[108:111], v[194:197], v[190:193], v[178:181]
	v_mfma_f32_16x16x32_bf16 v[76:79], v[92:95], v[232:235], v[76:79]
	v_mfma_f32_16x16x32_bf16 v[108:111], v[206:209], v[232:235], v[108:111]
	s_branch .Lcb_skip7
.Lcb_no7:
	v_mfma_f32_16x16x32_bf16 v[76:79], v[96:99], v[190:193], v[76:79]
	v_mfma_f32_16x16x32_bf16 v[76:79], v[92:95], v[232:235], v[76:79]
